# causal-conv loops (ssd_s1, ssd_s3 B/X): tap rows requested two rows ahead with alternating landing registers
# baseline (speedup 1.0000x reference)
.LBB0_621:
	s_or_b64 exec, exec, s[30:31]
	s_waitcnt lgkmcnt(0)
	s_barrier
	s_and_saveexec_b64 s[30:31], s[24:25]
	s_cbranch_execz .LBB0_634
	v_readlane_b32 s4, v242, 22
	v_readlane_b32 s5, v242, 23
	s_lshl_b64 s[4:5], s[4:5], 2
	v_readlane_b32 s50, v242, 24
	s_add_u32 s4, s62, s4
	v_readlane_b32 s51, v242, 25
	s_addc_u32 s5, s63, s5
	s_lshl_b64 s[50:51], s[50:51], 2
	s_add_u32 s40, s40, s50
	s_addc_u32 s41, s41, s51
	s_lshl_b32 s38, s55, 7
	v_or_b32_e32 v46, s38, v69
	v_add_u32_e32 v2, s38, v144
	v_cndmask_b32_e64 v2, v2, v46, s[22:23]
	v_lshlrev_b32_e32 v24, 2, v2
	v_mov_b32_e32 v25, v11
	v_lshl_add_u64 v[28:29], s[4:5], 0, v[24:25]
	global_load_dwordx4 v[2:5], v24, s[40:41] offset:16
	global_load_dwordx4 v[6:9], v24, s[40:41]
	global_load_dwordx4 v[12:15], v24, s[4:5] offset:16
	global_load_dwordx4 v[16:19], v24, s[4:5]
	global_load_dwordx4 v[20:23], v24, s[4:5] offset:3088
	s_nop 0
	global_load_dwordx4 v[24:27], v24, s[4:5] offset:3072
	s_movk_i32 s4, 0x1000
	v_add_co_u32_e32 v30, vcc, s4, v28
	s_mov_b64 s[50:51], 0x1800
	s_nop 0
	v_addc_co_u32_e32 v31, vcc, 0, v29, vcc
	s_movk_i32 s4, 0x2000
	v_lshl_add_u64 v[36:37], v[28:29], 0, s[50:51]
	s_mov_b64 s[50:51], 0x2400
	v_add_co_u32_e32 v32, vcc, s4, v28
	v_lshl_add_u64 v[40:41], v[28:29], 0, s[50:51]
	s_nop 0
	v_addc_co_u32_e32 v33, vcc, 0, v29, vcc
	global_load_dwordx4 v[28:31], v[30:31], off offset:2048
	s_nop 0
	global_load_dwordx4 v[32:35], v[32:33], off offset:1024
	s_nop 0
	global_load_dwordx4 v[36:39], v[36:37], off offset:16
	s_nop 0
	global_load_dwordx4 v[40:43], v[40:41], off offset:16
	s_lshl_b32 s4, s96, 7
	s_lshr_b32 s40, s47, 7
	s_mov_b32 s41, s49
	s_and_b32 s4, s4, 0x3f00
	s_lshl_b64 s[40:41], s[40:41], 14
	v_or_b32_e32 v46, 0x800, v46
	v_add_u32_e32 v47, s38, v146
	s_or_b32 s40, s40, s4
	v_cndmask_b32_e64 v46, v47, v46, s[22:23]
	ds_read_b32 v54, v145 offset:1020
	v_lshl_add_u64 v[44:45], s[40:41], 0, v[70:71]
	v_lshlrev_b32_e32 v46, 1, v46
	v_mov_b32_e32 v47, v11
	v_mad_u64_u32 v[46:47], s[40:41], v44, s64, v[46:47]
	v_mad_i32_i24 v47, v45, s64, v47
	v_lshl_add_u64 v[44:45], s[34:35], 0, v[46:47]
	s_mov_b64 s[40:41], 0x97fb800
	v_lshl_add_u64 v[44:45], v[44:45], 0, s[40:41]
	s_mov_b64 s[40:41], 0
	v_mov_b32_e32 v55, v158
	v_mov_b32_e32 v56, v157
	v_mov_b32_e32 v57, v70
	s_add_u32 s98, s94, s94
	s_addc_u32 s99, s95, s95
	s_add_u32 s98, s98, 0x1000
	s_addc_u32 s99, s99, 0
	v_mov_b32_e32 v236, 0x3000
	v_mov_b32_e32 v237, 0
	v_add_co_u32_e32 v198, vcc, 0x1000, v44
	s_nop 1
	v_addc_co_u32_e32 v199, vcc, 0, v45, vcc
	v_add_co_u32_e32 v200, vcc, 0x4000, v44
	s_nop 1
	v_addc_co_u32_e32 v201, vcc, 0, v45, vcc
	global_load_dwordx4 v[214:217], v[198:199], off offset:-4096
	global_load_dwordx4 v[218:221], v[198:199], off offset:2048
	global_load_dwordx4 v[222:225], v[200:201], off offset:-4096
	global_load_dwordx4 v[226:229], v[200:201], off offset:2048
	v_lshl_add_u64 v[198:199], v[198:199], 0, s[94:95]
	v_lshl_add_u64 v[200:201], v[200:201], 0, s[94:95]
	global_load_dwordx4 v[230:233], v[198:199], off offset:-4096
	global_load_dwordx4 v[244:247], v[198:199], off offset:2048
	global_load_dwordx4 v[248:251], v[200:201], off offset:-4096
	global_load_dwordx4 v[252:255], v[200:201], off offset:2048
	s_mov_b32 s32, 1
	s_branch .LBB0_624

.LBB0_624:
	s_xor_b32 s32, s32, 1
	s_cmp_lg_u32 s32, 0
	s_cbranch_scc1 cvs_odd
	s_waitcnt vmcnt(4)
	v_mov_b64_e32 v[182:183], v[214:215]
	v_mov_b64_e32 v[184:185], v[216:217]
	v_mov_b64_e32 v[186:187], v[218:219]
	v_mov_b64_e32 v[188:189], v[220:221]
	v_mov_b64_e32 v[190:191], v[222:223]
	v_mov_b64_e32 v[192:193], v[224:225]
	v_mov_b64_e32 v[194:195], v[226:227]
	v_mov_b64_e32 v[196:197], v[228:229]
	v_lshl_add_u64 v[198:199], v[44:45], 0, s[98:99]
	v_lshl_add_u64 v[200:201], v[198:199], 0, v[236:237]
	global_load_dwordx4 v[214:217], v[198:199], off offset:-4096
	global_load_dwordx4 v[218:221], v[198:199], off offset:2048
	global_load_dwordx4 v[222:225], v[200:201], off offset:-4096
	global_load_dwordx4 v[226:229], v[200:201], off offset:2048
	s_branch cvs_join
cvs_odd:
	s_waitcnt vmcnt(4)
	v_mov_b64_e32 v[182:183], v[230:231]
	v_mov_b64_e32 v[184:185], v[232:233]
	v_mov_b64_e32 v[186:187], v[244:245]
	v_mov_b64_e32 v[188:189], v[246:247]
	v_mov_b64_e32 v[190:191], v[248:249]
	v_mov_b64_e32 v[192:193], v[250:251]
	v_mov_b64_e32 v[194:195], v[252:253]
	v_mov_b64_e32 v[196:197], v[254:255]
	v_lshl_add_u64 v[198:199], v[44:45], 0, s[98:99]
	v_lshl_add_u64 v[200:201], v[198:199], 0, v[236:237]
	global_load_dwordx4 v[230:233], v[198:199], off offset:-4096
	global_load_dwordx4 v[244:247], v[198:199], off offset:2048
	global_load_dwordx4 v[248:251], v[200:201], off offset:-4096
	global_load_dwordx4 v[252:255], v[200:201], off offset:2048
cvs_join:
	v_add_u32_e32 v58, s4, v57
	v_cmp_lt_i32_e32 vcc, 2, v58
	v_mov_b64_e32 v[52:53], v[6:7]
	v_mov_b64_e32 v[50:51], v[8:9]
	v_mov_b64_e32 v[48:49], v[2:3]
	v_mov_b64_e32 v[46:47], v[4:5]
	s_and_saveexec_b64 s[62:63], vcc
	s_cbranch_execnz .LBB0_631
	s_or_b64 exec, exec, s[62:63]
	v_cmp_lt_i32_e32 vcc, 1, v58
	s_and_saveexec_b64 s[62:63], vcc
	s_cbranch_execnz .LBB0_632

.LBB0_2269:
	s_or_b64 exec, exec, s[30:31]
	v_cndmask_b32_e64 v2, 0, 1, s[34:35]
	s_lshr_b32 s4, s2, 1
	v_lshlrev_b32_e32 v58, 8, v2
	v_or_b32_e32 v2, s96, v129
	s_and_b32 s4, s4, 63
	v_lshlrev_b32_e32 v10, 2, v2
	s_lshl_b32 s30, s4, 8
	v_lshl_add_u64 v[46:47], s[28:29], 0, v[10:11]
	v_lshl_add_u64 v[44:45], s[26:27], 0, v[10:11]
	s_waitcnt lgkmcnt(0)
	s_barrier
	s_and_saveexec_b64 s[16:17], s[8:9]
	s_cbranch_execz .LBB0_2280
	s_mov_b64 s[4:5], 0x400
	v_lshl_add_u64 v[24:25], v[44:45], 0, s[4:5]
	s_mov_b64 s[4:5], 0x1c00
	v_lshl_add_u64 v[36:37], v[44:45], 0, s[4:5]
	s_mov_b64 s[4:5], 0x2800
	v_lshl_add_u64 v[40:41], v[44:45], 0, s[4:5]
	s_movk_i32 s4, 0x1000
	v_add_co_u32_e32 v28, vcc, s4, v44
	s_movk_i32 s4, 0x2000
	s_nop 0
	v_addc_co_u32_e32 v29, vcc, 0, v45, vcc
	global_load_dwordx4 v[2:5], v[46:47], off offset:1040
	global_load_dwordx4 v[6:9], v[46:47], off offset:1024
	global_load_dwordx4 v[12:15], v[44:45], off offset:1040
	global_load_dwordx4 v[16:19], v[44:45], off offset:1024
	global_load_dwordx4 v[20:23], v[24:25], off offset:3088
	s_nop 0
	global_load_dwordx4 v[24:27], v[24:25], off offset:3072
	v_add_co_u32_e32 v32, vcc, s4, v44
	s_add_u32 s4, s30, s24
	s_nop 0
	v_addc_co_u32_e32 v33, vcc, 0, v45, vcc
	global_load_dwordx4 v[28:31], v[28:29], off offset:3072
	s_nop 0
	global_load_dwordx4 v[32:35], v[32:33], off offset:2048
	s_nop 0
	global_load_dwordx4 v[36:39], v[36:37], off offset:16
	s_nop 0
	global_load_dwordx4 v[40:43], v[40:41], off offset:16
	s_addc_u32 s5, 0, s25
	v_lshl_add_u64 v[50:51], s[4:5], 0, v[68:69]
	v_mad_u64_u32 v[52:53], s[4:5], v50, s64, 0
	v_lshl_add_u64 v[48:49], s[90:91], 0, v[72:73]
	v_mad_i32_i24 v51, v51, s64, v53
	v_or_b32_e32 v50, v52, v58
	v_lshl_add_u64 v[48:49], v[48:49], 0, v[50:51]
	s_mov_b64 s[4:5], 0x97fca00
	v_lshl_add_u64 v[48:49], v[48:49], 0, s[4:5]
	s_mov_b64 s[26:27], 0
	v_mov_b32_e32 v10, v136
	v_mov_b32_e32 v59, v68
	s_add_u32 s50, s60, s60
	s_addc_u32 s51, s61, s61
	s_add_u32 s50, s50, 0x1000
	s_addc_u32 s51, s51, 0
	s_add_u32 s98, s60, s60
	s_addc_u32 s99, s61, s61
	s_add_u32 s98, s98, 0x4000
	s_addc_u32 s99, s99, 0
	v_add_co_u32_e32 v198, vcc, 0x1000, v48
	s_nop 1
	v_addc_co_u32_e32 v199, vcc, 0, v49, vcc
	v_add_co_u32_e32 v200, vcc, 0x4000, v48
	s_nop 1
	v_addc_co_u32_e32 v201, vcc, 0, v49, vcc
	global_load_dwordx4 v[150:153], v[198:199], off offset:-4096
	global_load_dwordx4 v[154:157], v[198:199], off offset:2048
	global_load_dwordx4 v[158:161], v[200:201], off offset:-4096
	global_load_dwordx4 v[162:165], v[200:201], off offset:2048
	v_lshl_add_u64 v[198:199], v[198:199], 0, s[60:61]
	v_lshl_add_u64 v[200:201], v[200:201], 0, s[60:61]
	global_load_dwordx4 v[214:217], v[198:199], off offset:-4096
	global_load_dwordx4 v[218:221], v[198:199], off offset:2048
	global_load_dwordx4 v[222:225], v[200:201], off offset:-4096
	global_load_dwordx4 v[226:229], v[200:201], off offset:2048
	s_mov_b32 s32, 1
	s_branch .LBB0_2272

.LBB0_2272:
	s_xor_b32 s32, s32, 1
	s_cmp_lg_u32 s32, 0
	s_cbranch_scc1 cvb_odd
	s_waitcnt vmcnt(4)
	v_mov_b64_e32 v[182:183], v[150:151]
	v_mov_b64_e32 v[184:185], v[152:153]
	v_mov_b64_e32 v[186:187], v[154:155]
	v_mov_b64_e32 v[188:189], v[156:157]
	v_mov_b64_e32 v[190:191], v[158:159]
	v_mov_b64_e32 v[192:193], v[160:161]
	v_mov_b64_e32 v[194:195], v[162:163]
	v_mov_b64_e32 v[196:197], v[164:165]
	v_lshl_add_u64 v[198:199], v[48:49], 0, s[50:51]
	v_lshl_add_u64 v[200:201], v[48:49], 0, s[98:99]
	global_load_dwordx4 v[150:153], v[198:199], off offset:-4096
	global_load_dwordx4 v[154:157], v[198:199], off offset:2048
	global_load_dwordx4 v[158:161], v[200:201], off offset:-4096
	global_load_dwordx4 v[162:165], v[200:201], off offset:2048
	s_branch cvb_join
cvb_odd:
	s_waitcnt vmcnt(4)
	v_mov_b64_e32 v[182:183], v[214:215]
	v_mov_b64_e32 v[184:185], v[216:217]
	v_mov_b64_e32 v[186:187], v[218:219]
	v_mov_b64_e32 v[188:189], v[220:221]
	v_mov_b64_e32 v[190:191], v[222:223]
	v_mov_b64_e32 v[192:193], v[224:225]
	v_mov_b64_e32 v[194:195], v[226:227]
	v_mov_b64_e32 v[196:197], v[228:229]
	v_lshl_add_u64 v[198:199], v[48:49], 0, s[50:51]
	v_lshl_add_u64 v[200:201], v[48:49], 0, s[98:99]
	global_load_dwordx4 v[214:217], v[198:199], off offset:-4096
	global_load_dwordx4 v[218:221], v[198:199], off offset:2048
	global_load_dwordx4 v[222:225], v[200:201], off offset:-4096
	global_load_dwordx4 v[226:229], v[200:201], off offset:2048
cvb_join:
	v_add_u32_e32 v60, s30, v59
	v_cmp_lt_i32_e32 vcc, 2, v60
	v_mov_b64_e32 v[50:51], v[4:5]
	v_mov_b64_e32 v[52:53], v[2:3]
	v_mov_b64_e32 v[54:55], v[8:9]
	v_mov_b64_e32 v[56:57], v[6:7]
	s_and_saveexec_b64 s[28:29], vcc
	s_cbranch_execnz .LBB0_2276
	s_or_b64 exec, exec, s[28:29]
	v_cmp_lt_i32_e32 vcc, 1, v60
	s_and_saveexec_b64 s[28:29], vcc
	s_cbranch_execnz .LBB0_2277

.LBB0_2280:
	s_waitcnt vmcnt(0)
	s_or_b64 exec, exec, s[16:17]
	s_and_saveexec_b64 s[16:17], s[8:9]
	s_cbranch_execz .LBB0_2291
	s_mov_b64 s[4:5], 0x1800
	s_waitcnt vmcnt(1)
	v_lshl_add_u64 v[36:37], v[44:45], 0, s[4:5]
	s_mov_b64 s[4:5], 0x2400
	s_waitcnt vmcnt(0)
	v_lshl_add_u64 v[40:41], v[44:45], 0, s[4:5]
	s_movk_i32 s4, 0x1000
	v_add_co_u32_e32 v28, vcc, s4, v44
	s_movk_i32 s4, 0x2000
	s_nop 0
	v_addc_co_u32_e32 v29, vcc, 0, v45, vcc
	global_load_dwordx4 v[2:5], v[46:47], off offset:16
	global_load_dwordx4 v[6:9], v[46:47], off
	global_load_dwordx4 v[12:15], v[44:45], off offset:16
	global_load_dwordx4 v[16:19], v[44:45], off
	global_load_dwordx4 v[20:23], v[44:45], off offset:3088
	global_load_dwordx4 v[24:27], v[44:45], off offset:3072
	v_add_co_u32_e32 v32, vcc, s4, v44
	s_add_u32 s4, s30, s24
	s_nop 0
	v_addc_co_u32_e32 v33, vcc, 0, v45, vcc
	global_load_dwordx4 v[28:31], v[28:29], off offset:2048
	s_nop 0
	global_load_dwordx4 v[32:35], v[32:33], off offset:1024
	s_nop 0
	global_load_dwordx4 v[36:39], v[36:37], off offset:16
	s_nop 0
	global_load_dwordx4 v[40:43], v[40:41], off offset:16
	s_addc_u32 s5, 0, s25
	v_lshl_add_u64 v[46:47], s[4:5], 0, v[68:69]
	v_mad_u64_u32 v[48:49], s[4:5], v46, s64, 0
	v_lshl_add_u64 v[44:45], s[90:91], 0, v[72:73]
	v_mad_i32_i24 v47, v47, s64, v49
	v_or_b32_e32 v46, v48, v58
	v_lshl_add_u64 v[44:45], v[44:45], 0, v[46:47]
	s_mov_b64 s[4:5], 0x97fc800
	v_lshl_add_u64 v[44:45], v[44:45], 0, s[4:5]
	s_mov_b64 s[24:25], 0
	v_mov_b32_e32 v10, v138
	v_mov_b32_e32 v54, v137
	v_mov_b32_e32 v55, v68
	s_add_u32 s50, s60, s60
	s_addc_u32 s51, s61, s61
	s_add_u32 s50, s50, 0x1000
	s_addc_u32 s51, s51, 0
	s_add_u32 s98, s60, s60
	s_addc_u32 s99, s61, s61
	s_add_u32 s98, s98, 0x4000
	s_addc_u32 s99, s99, 0
	v_add_co_u32_e32 v198, vcc, 0x1000, v44
	s_nop 1
	v_addc_co_u32_e32 v199, vcc, 0, v45, vcc
	v_add_co_u32_e32 v200, vcc, 0x4000, v44
	s_nop 1
	v_addc_co_u32_e32 v201, vcc, 0, v45, vcc
	global_load_dwordx4 v[150:153], v[198:199], off offset:-4096
	global_load_dwordx4 v[154:157], v[198:199], off offset:2048
	global_load_dwordx4 v[158:161], v[200:201], off offset:-4096
	global_load_dwordx4 v[162:165], v[200:201], off offset:2048
	v_lshl_add_u64 v[198:199], v[198:199], 0, s[60:61]
	v_lshl_add_u64 v[200:201], v[200:201], 0, s[60:61]
	global_load_dwordx4 v[214:217], v[198:199], off offset:-4096
	global_load_dwordx4 v[218:221], v[198:199], off offset:2048
	global_load_dwordx4 v[222:225], v[200:201], off offset:-4096
	global_load_dwordx4 v[226:229], v[200:201], off offset:2048
	s_mov_b32 s32, 1
	s_branch .LBB0_2283

.LBB0_2283:
	s_xor_b32 s32, s32, 1
	s_cmp_lg_u32 s32, 0
	s_cbranch_scc1 cvx_odd
	s_waitcnt vmcnt(4)
	v_mov_b64_e32 v[182:183], v[150:151]
	v_mov_b64_e32 v[184:185], v[152:153]
	v_mov_b64_e32 v[186:187], v[154:155]
	v_mov_b64_e32 v[188:189], v[156:157]
	v_mov_b64_e32 v[190:191], v[158:159]
	v_mov_b64_e32 v[192:193], v[160:161]
	v_mov_b64_e32 v[194:195], v[162:163]
	v_mov_b64_e32 v[196:197], v[164:165]
	v_lshl_add_u64 v[198:199], v[44:45], 0, s[50:51]
	v_lshl_add_u64 v[200:201], v[44:45], 0, s[98:99]
	global_load_dwordx4 v[150:153], v[198:199], off offset:-4096
	global_load_dwordx4 v[154:157], v[198:199], off offset:2048
	global_load_dwordx4 v[158:161], v[200:201], off offset:-4096
	global_load_dwordx4 v[162:165], v[200:201], off offset:2048
	s_branch cvx_join
cvx_odd:
	s_waitcnt vmcnt(4)
	v_mov_b64_e32 v[182:183], v[214:215]
	v_mov_b64_e32 v[184:185], v[216:217]
	v_mov_b64_e32 v[186:187], v[218:219]
	v_mov_b64_e32 v[188:189], v[220:221]
	v_mov_b64_e32 v[190:191], v[222:223]
	v_mov_b64_e32 v[192:193], v[224:225]
	v_mov_b64_e32 v[194:195], v[226:227]
	v_mov_b64_e32 v[196:197], v[228:229]
	v_lshl_add_u64 v[198:199], v[44:45], 0, s[50:51]
	v_lshl_add_u64 v[200:201], v[44:45], 0, s[98:99]
	global_load_dwordx4 v[214:217], v[198:199], off offset:-4096
	global_load_dwordx4 v[218:221], v[198:199], off offset:2048
	global_load_dwordx4 v[222:225], v[200:201], off offset:-4096
	global_load_dwordx4 v[226:229], v[200:201], off offset:2048
cvx_join:
	v_add_u32_e32 v56, s30, v55
	v_cmp_lt_i32_e32 vcc, 2, v56
	v_mov_b64_e32 v[46:47], v[4:5]
	v_mov_b64_e32 v[48:49], v[2:3]
	v_mov_b64_e32 v[50:51], v[8:9]
	v_mov_b64_e32 v[52:53], v[6:7]
	s_and_saveexec_b64 s[26:27], vcc
	s_cbranch_execnz .LBB0_2287
	s_or_b64 exec, exec, s[26:27]
	v_cmp_lt_i32_e32 vcc, 1, v56
	s_and_saveexec_b64 s[26:27], vcc
	s_cbranch_execnz .LBB0_2288
